# v31: v30 + P5 state update: LDS fragment reads of step k+1 in flight during step k (two register sets)
# speedup vs baseline: 1.0061x; 1.0061x over previous
; #define LAS __attribute__((address_space(3)))
; DI unsigned pk2(float lo, float hi) { f32x2 v = {lo, hi}; bfv2 b = __builtin_convertvector(v, bfv2); return __builtin_bit_cast(unsigned, b); }
; DI bf16_t f2bf(float x) { return (bf16_t)(pk2(x, 0.f) & 0xffffu); }
; #define MFMA16(a, b, c) __builtin_amdgcn_mfma_f32_16x16x32_bf16((a), (b), (c), 0, 0, 0)
; template <bool OUT> DI void hgrn_item(LAS unsigned char* lds, bf16_t* proj, float* hst, float* hdv, const float* normw, int item, bool dry) {
;     ...
;                 for (int r = 0; r < 4; ++r) { const int tt = 16 * ti + 4 * rq + r, ss = 16 * sj + e16; Ab[tt * TP + ss] = (sj <= ti && ss <= tt) ? f2bf(a[r]) : (bf16_t)0; }
;             }
; #pragma unroll
;             for (int ti = 0; ti < 4; ++ti) { o[ti] = (f32x4){0.f, 0.f, 0.f, 0.f};
; #pragma unroll
;                 for (int ks = 0; ks < 4; ++ks) { const LAS bf16_t* qp = Qt + (16 * ti + e16) * QP + 32 * ks + 4 * rq; const u32x2 q0 = *(const LAS u32x2*)qp, q1 = *(const LAS u32x2*)(qp + 16);
;                     u32x4 qa = {q0.x, q0.y, q1.x, q1.y};
;                     u32x4 sb; sb.x = pk2(st[2 * ks][0], st[2 * ks][1]); sb.y = pk2(st[2 * ks][2], st[2 * ks][3]); sb.z = pk2(st[2 * ks + 1][0], st[2 * ks + 1][1]); sb.w = pk2(st[2 * ks + 1][2], st[2 * ks + 1][3]);
;                     o[ti] = MFMA16(__builtin_bit_cast(bf16x8, qa), __builtin_bit_cast(bf16x8, sb), o[ti]); } }
;         }
; #pragma unroll
;         for (int dt = 0; dt < 8; ++dt) {
; #pragma unroll
;             for (int ks = 0; ks < 2; ++ks) { const bf16x8 ka = *(const LAS bf16x8*)(KtT + (16 * dt + e16) * TP + 32 * ks + 8 * rq); st[dt] = MFMA16(ka, vfr[ks], st[dt]); }
;             const f32x4 dv = *(const LAS f32x4*)(Dv + 16 * dt + 4 * rq);
;             st[dt] *= dv;
;         }
.LBB0_1170:
	v_or_b32_e32 v56, s14, v104
	v_cmp_gt_u32_e32 vcc, v120, v56
	s_or_b64 s[36:37], s[20:21], vcc
	s_nop 3
	v_cvt_pk_bf16_f32 v50, v50, s0
	v_cndmask_b32_e64 v50, v50, 0, s[36:37]
	v_mad_u64_u32 v[54:55], s[36:37], v56, s39, v[92:93]
	ds_write_b16 v54, v50
	v_or_b32_e32 v50, 1, v56
	v_cmp_gt_u32_e32 vcc, v120, v50
	s_or_b64 s[36:37], s[20:21], vcc
	v_cvt_pk_bf16_f32 v50, v51, s0
	v_cndmask_b32_e64 v50, v50, 0, s[36:37]
	ds_write_b16 v54, v50 offset:144
	v_or_b32_e32 v50, 2, v56
	v_cmp_gt_u32_e32 vcc, v120, v50
	s_or_b64 s[36:37], s[20:21], vcc
	v_cvt_pk_bf16_f32 v50, v52, s0
	v_cndmask_b32_e64 v50, v50, 0, s[36:37]
	ds_write_b16 v54, v50 offset:288
	v_or_b32_e32 v50, 3, v56
	v_cmp_gt_u32_e32 vcc, v120, v50
	s_or_b64 s[36:37], s[20:21], vcc
	v_cvt_pk_bf16_f32 v50, v53, s0
	v_cndmask_b32_e64 v50, v50, 0, s[36:37]
	ds_write_b16 v54, v50 offset:432
	ds_read2_b64 v[50:53], v115 offset1:4
	ds_read2_b64 v[54:57], v115 offset0:8 offset1:12
	s_waitcnt vmcnt(7)
	v_cvt_pk_bf16_f32 v66, v6, v7
	v_cvt_pk_bf16_f32 v67, v8, v9
	s_waitcnt vmcnt(6)
	v_cvt_pk_bf16_f32 v68, v10, v11
	v_cvt_pk_bf16_f32 v69, v12, v13
	s_waitcnt vmcnt(5)
	v_cvt_pk_bf16_f32 v70, v2, v3
	v_cvt_pk_bf16_f32 v71, v4, v5
	s_waitcnt lgkmcnt(1)
	v_mfma_f32_16x16x32_bf16 v[50:53], v[50:53], v[66:69], 0
	s_waitcnt vmcnt(4)
	v_cvt_pk_bf16_f32 v72, v18, v19
	v_cvt_pk_bf16_f32 v73, v20, v21
	s_waitcnt vmcnt(3)
	v_cvt_pk_bf16_f32 v100, v14, v15
	v_cvt_pk_bf16_f32 v101, v16, v17
	s_waitcnt lgkmcnt(0)
	v_mfma_f32_16x16x32_bf16 v[50:53], v[54:57], v[70:73], v[50:53]
	ds_read2_b64 v[54:57], v115 offset0:16 offset1:20
	s_waitcnt vmcnt(2)
	v_cvt_pk_bf16_f32 v102, v26, v27
	v_cvt_pk_bf16_f32 v103, v28, v29
	s_waitcnt vmcnt(1)
	v_cvt_pk_bf16_f32 v144, v22, v23
	v_cvt_pk_bf16_f32 v145, v24, v25
	s_waitcnt lgkmcnt(0)
	v_mfma_f32_16x16x32_bf16 v[50:53], v[54:57], v[100:103], v[50:53]
	ds_read2_b64 v[54:57], v115 offset0:24 offset1:28
	s_waitcnt vmcnt(0)
	v_cvt_pk_bf16_f32 v146, v30, v31
	v_cvt_pk_bf16_f32 v147, v32, v33
	v_add_u32_e32 v62, 0x1000, v115
	ds_read2_b64 v[58:61], v62 offset0:40 offset1:44
	s_waitcnt lgkmcnt(1)
	v_mfma_f32_16x16x32_bf16 v[54:57], v[54:57], v[144:147], v[50:53]
	s_nop 2
	ds_read2_b64 v[50:53], v62 offset0:32 offset1:36
	v_add_u32_e32 v143, 0x2000, v115
	s_waitcnt lgkmcnt(0)
	v_mfma_f32_16x16x32_bf16 v[50:53], v[50:53], v[66:69], 0
	v_mfma_f32_16x16x32_bf16 v[50:53], v[58:61], v[70:73], v[50:53]
	ds_read2_b64 v[58:61], v62 offset0:48 offset1:52
	s_waitcnt lgkmcnt(0)
	v_mfma_f32_16x16x32_bf16 v[50:53], v[58:61], v[100:103], v[50:53]
	ds_read2_b64 v[58:61], v62 offset0:56 offset1:60
	ds_read2_b64 v[62:65], v143 offset0:72 offset1:76
	s_waitcnt lgkmcnt(1)
	v_mfma_f32_16x16x32_bf16 v[58:61], v[58:61], v[144:147], v[50:53]
	s_nop 3
	ds_read2_b64 v[50:53], v143 offset0:64 offset1:68
	s_waitcnt lgkmcnt(0)
	v_mfma_f32_16x16x32_bf16 v[50:53], v[50:53], v[66:69], 0
	v_mfma_f32_16x16x32_bf16 v[50:53], v[62:65], v[70:73], v[50:53]
	ds_read2_b64 v[62:65], v143 offset0:80 offset1:84
	s_waitcnt lgkmcnt(0)
	v_mfma_f32_16x16x32_bf16 v[50:53], v[62:65], v[100:103], v[50:53]
	ds_read2_b64 v[62:65], v143 offset0:88 offset1:92
	v_add_u32_e32 v143, 0x3000, v115
	s_waitcnt lgkmcnt(0)
	v_mfma_f32_16x16x32_bf16 v[62:65], v[62:65], v[144:147], v[50:53]
	s_nop 3
	ds_read2_b64 v[50:53], v143 offset0:96 offset1:100
	s_waitcnt lgkmcnt(0)
	v_mfma_f32_16x16x32_bf16 v[50:53], v[50:53], v[66:69], 0
	ds_read2_b64 v[66:69], v143 offset0:104 offset1:108
	s_waitcnt lgkmcnt(0)
	v_mfma_f32_16x16x32_bf16 v[50:53], v[66:69], v[70:73], v[50:53]
	ds_read2_b64 v[66:69], v143 offset0:112 offset1:116
	s_waitcnt lgkmcnt(0)
	v_mfma_f32_16x16x32_bf16 v[50:53], v[66:69], v[100:103], v[50:53]
	ds_read2_b64 v[66:69], v143 offset0:120 offset1:124
	v_lshl_add_u64 v[102:103], v[98:99], 0, s[34:35]
	v_lshl_add_u64 v[100:101], v[96:97], 0, s[34:35]
	s_waitcnt lgkmcnt(0)
	v_mfma_f32_16x16x32_bf16 v[70:73], v[66:69], v[144:147], v[50:53]
	v_add_u32_e32 v66, v93, v108
	s_nop 1
	v_add_u32_e32 v67, 0x13c00, v93
	ds_read_b128 v[50:53], v66 offset:34816
	ds_read_b128 v[162:165], v66 offset:34880
	ds_read_b128 v[166:169], v67
	s_add_u32 s34, s34, 0xc8000
	s_addc_u32 s35, s35, 0
	s_cmp_lg_u32 s34, 0x320000
	ds_read_b128 v[170:173], v66 offset:37120
	ds_read_b128 v[174:177], v66 offset:37184
	ds_read_b128 v[178:181], v67 offset:64
	s_waitcnt lgkmcnt(3)
	v_mfma_f32_16x16x32_bf16 v[6:9], v[50:53], v[46:49], v[6:9]
	v_mfma_f32_16x16x32_bf16 v[6:9], v[162:165], v[42:45], v[6:9]
	s_nop 7
	v_pk_mul_f32 v[8:9], v[8:9], v[168:169]
	v_pk_mul_f32 v[6:7], v[6:7], v[166:167]
	ds_read_b128 v[50:53], v66 offset:39424
	ds_read_b128 v[162:165], v66 offset:39488
	ds_read_b128 v[166:169], v67 offset:128
	s_waitcnt lgkmcnt(3)
	v_mfma_f32_16x16x32_bf16 v[10:13], v[170:173], v[46:49], v[10:13]
	v_mfma_f32_16x16x32_bf16 v[10:13], v[174:177], v[42:45], v[10:13]
	s_nop 7
	v_pk_mul_f32 v[12:13], v[12:13], v[180:181]
	v_pk_mul_f32 v[10:11], v[10:11], v[178:179]
	ds_read_b128 v[170:173], v66 offset:41728
	ds_read_b128 v[174:177], v66 offset:41792
	ds_read_b128 v[178:181], v67 offset:192
	s_waitcnt lgkmcnt(3)
	v_mfma_f32_16x16x32_bf16 v[2:5], v[50:53], v[46:49], v[2:5]
	v_mfma_f32_16x16x32_bf16 v[2:5], v[162:165], v[42:45], v[2:5]
	s_nop 7
	v_pk_mul_f32 v[4:5], v[4:5], v[168:169]
	v_pk_mul_f32 v[2:3], v[2:3], v[166:167]
	ds_read_b128 v[50:53], v66 offset:44032
	ds_read_b128 v[162:165], v66 offset:44096
	ds_read_b128 v[166:169], v67 offset:256
	s_waitcnt lgkmcnt(3)
	v_mfma_f32_16x16x32_bf16 v[18:21], v[170:173], v[46:49], v[18:21]
	v_mfma_f32_16x16x32_bf16 v[18:21], v[174:177], v[42:45], v[18:21]
	s_nop 7
	v_pk_mul_f32 v[20:21], v[20:21], v[180:181]
	v_pk_mul_f32 v[18:19], v[18:19], v[178:179]
	ds_read_b128 v[170:173], v66 offset:46336
	ds_read_b128 v[174:177], v66 offset:46400
	ds_read_b128 v[178:181], v67 offset:320
	s_waitcnt lgkmcnt(3)
; #define LAS __attribute__((address_space(3)))
; #define MFMA16(a, b, c) __builtin_amdgcn_mfma_f32_16x16x32_bf16((a), (b), (c), 0, 0, 0)
; template <bool OUT> DI void hgrn_item(LAS unsigned char* lds, bf16_t* proj, float* hst, float* hdv, const float* normw, int item, bool dry) {
;     ...
; #pragma unroll
;         for (int dt = 0; dt < 8; ++dt) {
; #pragma unroll
;             for (int ks = 0; ks < 2; ++ks) { const bf16x8 ka = *(const LAS bf16x8*)(KtT + (16 * dt + e16) * TP + 32 * ks + 8 * rq); st[dt] = MFMA16(ka, vfr[ks], st[dt]); }
;             const f32x4 dv = *(const LAS f32x4*)(Dv + 16 * dt + 4 * rq);
;             st[dt] *= dv;
;         }
;         u32x4 gate8[2];
;         if (OUT) {
; #pragma unroll
;             for (int j = 0; j < 2; ++j) { const int cch = tid + 512 * j; gate8[j] = *(const u32x4*)(proj + (row0 + (cch >> 4)) * NPJ + C_HG + h * 128 + 8 * (cch & 15)); }
;         }
;         __syncthreads();
;         if (OUT) {
; #pragma unroll
;             for (int ti = 0; ti < 4; ++ti)
; #pragma unroll
;                 for (int ks = 0; ks < 2; ++ks) if (2 * ks <= ti) { const bf16x8 aa = *(const LAS bf16x8*)(Ab + (16 * ti + e16) * TP + 32 * ks + 8 * rq); o[ti] = MFMA16(aa, vfr[ks], o[ti]); }
;             LAS float* Ob = (LAS float*)(lds + HOB_OFF);
; #pragma unroll
;             for (int ti = 0; ti < 4; ++ti)
; #pragma unroll
;                 for (int r = 0; r < 4; ++r) Ob[(16 * ti + 4 * rq + r) * OBP + w * 16 + e16] = o[ti][r];
	v_mfma_f32_16x16x32_bf16 v[14:17], v[50:53], v[46:49], v[14:17]
	v_mfma_f32_16x16x32_bf16 v[14:17], v[162:165], v[42:45], v[14:17]
	s_nop 7
	v_pk_mul_f32 v[16:17], v[16:17], v[168:169]
	v_pk_mul_f32 v[14:15], v[14:15], v[166:167]
	ds_read_b128 v[50:53], v66 offset:48640
	ds_read_b128 v[162:165], v66 offset:48704
	ds_read_b128 v[166:169], v67 offset:384
	s_waitcnt lgkmcnt(3)
	v_mfma_f32_16x16x32_bf16 v[26:29], v[170:173], v[46:49], v[26:29]
	v_mfma_f32_16x16x32_bf16 v[26:29], v[174:177], v[42:45], v[26:29]
	s_nop 7
	v_pk_mul_f32 v[28:29], v[28:29], v[180:181]
	v_pk_mul_f32 v[26:27], v[26:27], v[178:179]
	ds_read_b128 v[170:173], v66 offset:50944
	ds_read_b128 v[174:177], v66 offset:51008
	ds_read_b128 v[178:181], v67 offset:448
	s_waitcnt lgkmcnt(3)
	v_mfma_f32_16x16x32_bf16 v[22:25], v[50:53], v[46:49], v[22:25]
	v_mfma_f32_16x16x32_bf16 v[22:25], v[162:165], v[42:45], v[22:25]
	s_nop 7
	v_pk_mul_f32 v[24:25], v[24:25], v[168:169]
	v_pk_mul_f32 v[22:23], v[22:23], v[166:167]
	s_waitcnt lgkmcnt(0)
	v_mfma_f32_16x16x32_bf16 v[30:33], v[170:173], v[46:49], v[30:33]
	v_mfma_f32_16x16x32_bf16 v[30:33], v[174:177], v[42:45], v[30:33]
	s_nop 7
	v_pk_mul_f32 v[32:33], v[32:33], v[180:181]
	v_pk_mul_f32 v[30:31], v[30:31], v[178:179]
	v_add_co_u32_e32 v50, vcc, s47, v102
	s_nop 0
	v_addc_co_u32_e32 v51, vcc, 0, v103, vcc
	global_load_dwordx4 v[66:69], v[50:51], off offset:512
	v_add_co_u32_e32 v50, vcc, s47, v100
	s_nop 1
	v_addc_co_u32_e32 v51, vcc, 0, v101, vcc
	global_load_dwordx4 v[50:53], v[50:51], off offset:512
	s_barrier
	ds_read_b128 v[144:147], v116
	s_waitcnt lgkmcnt(0)
	v_mfma_f32_16x16x32_bf16 v[54:57], v[144:147], v[46:49], v[54:57]
	ds_read_b128 v[144:147], v116 offset:2304
	s_waitcnt lgkmcnt(0)
	v_mfma_f32_16x16x32_bf16 v[58:61], v[144:147], v[46:49], v[58:61]
	ds_read_b128 v[144:147], v116 offset:4608
	s_waitcnt lgkmcnt(0)
	v_mfma_f32_16x16x32_bf16 v[62:65], v[144:147], v[46:49], v[62:65]
	ds_read_b128 v[144:147], v116 offset:4672
	s_waitcnt lgkmcnt(0)
	v_mfma_f32_16x16x32_bf16 v[62:65], v[144:147], v[42:45], v[62:65]
	ds_read_b128 v[144:147], v116 offset:6912
	s_waitcnt lgkmcnt(0)
	v_mfma_f32_16x16x32_bf16 v[46:49], v[144:147], v[46:49], v[70:73]
	s_nop 2
	ds_read_b128 v[70:73], v116 offset:6976
	ds_write2_b32 v125, v54, v55 offset1:132
	s_waitcnt lgkmcnt(1)
	v_mfma_f32_16x16x32_bf16 v[42:45], v[70:73], v[42:45], v[46:49]
	s_nop 2
	v_add_u32_e32 v46, 0x400, v125
	ds_write2_b32 v46, v56, v57 offset0:8 offset1:140
	v_add_u32_e32 v46, 0x2000, v125
	ds_write2_b32 v46, v58, v59 offset0:64 offset1:196
	v_add_u32_e32 v46, 0x2400, v125
	ds_write2_b32 v46, v60, v61 offset0:72 offset1:204
	v_add_u32_e32 v46, 0x4200, v125
	ds_write2_b32 v46, v62, v63 offset1:132
	v_add_u32_e32 v46, 0x4600, v125
	ds_write2_b32 v46, v64, v65 offset0:8 offset1:140
	v_add_u32_e32 v46, 0x6200, v125
	ds_write2_b32 v46, v42, v43 offset0:64 offset1:196
	v_add_u32_e32 v42, 0x6600, v125
	ds_write2_b32 v42, v44, v45 offset0:72 offset1:204
	s_waitcnt lgkmcnt(0)
	s_barrier
; #define LAS __attribute__((address_space(3)))
; DI float bflo(unsigned w) { return __uint_as_float(w << 16); }
; DI float bfhi(unsigned w) { return __uint_as_float(w & 0xffff0000u); }
; DI u32x4 pack8(f32x4 a, f32x4 b) { u32x4 w; w.x = pk2(a[0], a[1]); w.y = pk2(a[2], a[3]); w.z = pk2(b[0], b[1]); w.w = pk2(b[2], b[3]); return w; }
; template <bool OUT> DI void hgrn_item(LAS unsigned char* lds, bf16_t* proj, float* hst, float* hdv, const float* normw, int item, bool dry) {
;     ...
; #pragma unroll
;             for (int j = 0; j < 2; ++j) { const int cch = tid + 512 * j, tt = cch >> 4, e0 = 8 * (cch & 15);
;                 const f32x4 a0 = *(const LAS f32x4*)(Ob + tt * OBP + e0), a1 = *(const LAS f32x4*)(Ob + tt * OBP + e0 + 4);
;                 float q = (a0[0] * a0[0] + a0[1] * a0[1]) + (a0[2] * a0[2] + a0[3] * a0[3]) + (a1[0] * a1[0] + a1[1] * a1[1]) + (a1[2] * a1[2] + a1[3] * a1[3]);
;                 q += __shfl_xor(q, 1); q += __shfl_xor(q, 2); q += __shfl_xor(q, 4); q += __shfl_xor(q, 8);
;                 const float rs = __builtin_amdgcn_rsqf(q * (1.0f / 128.0f) + 1e-6f);
;                 const f32x4 n0 = *(const f32x4*)(normw + e0), n1 = *(const f32x4*)(normw + e0 + 4); const u32x4 g = gate8[j];
;                 f32x4 y0, y1;
;                 y0[0] = a0[0] * rs * n0[0] * bflo(g.x); y0[1] = a0[1] * rs * n0[1] * bfhi(g.x); y0[2] = a0[2] * rs * n0[2] * bflo(g.y); y0[3] = a0[3] * rs * n0[3] * bfhi(g.y);
;                 y1[0] = a1[0] * rs * n1[0] * bflo(g.z); y1[1] = a1[1] * rs * n1[1] * bfhi(g.z); y1[2] = a1[2] * rs * n1[2] * bflo(g.w); y1[3] = a1[3] * rs * n1[3] * bfhi(g.w);
;                 if (!dry) *(u32x4*)(proj + (row0 + tt) * NPJ + C_HQ + h * 128 + e0) = pack8(y0, y1); }
	ds_read_b128 v[42:45], v117
	ds_read_b128 v[46:49], v117 offset:16
	s_waitcnt vmcnt(1)
	v_lshlrev_b32_e32 v64, 16, v68
	v_and_b32_e32 v65, 0xffff0000, v68
	s_waitcnt lgkmcnt(1)
	v_pk_mul_f32 v[54:55], v[44:45], v[44:45]
	v_pk_mul_f32 v[56:57], v[42:43], v[42:43]
	s_nop 0
	v_pk_mov_b32 v[58:59], v[56:57], v[54:55] op_sel:[1,0]
	v_mov_b32_e32 v57, v55
	v_pk_add_f32 v[54:55], v[58:59], v[56:57]
	s_waitcnt lgkmcnt(0)
	v_pk_mul_f32 v[56:57], v[48:49], v[48:49]
	v_pk_mul_f32 v[58:59], v[46:47], v[46:47]
	v_mov_b32_e32 v60, v56
	v_mov_b32_e32 v61, v58
	v_mov_b32_e32 v58, v57
	v_pk_add_f32 v[56:57], v[60:61], v[58:59]
	v_add_f32_e32 v54, v54, v55
	v_add_f32_e32 v54, v54, v57
	v_add_f32_e32 v54, v56, v54
	s_nop 1
	v_add_f32_dpp v54, v54, v54 quad_perm:[1,0,3,2] row_mask:0xf bank_mask:0xf
	s_nop 1
	v_add_f32_dpp v54, v54, v54 quad_perm:[2,3,0,1] row_mask:0xf bank_mask:0xf
	s_nop 1
	v_add_f32_dpp v62, v54, v54 row_half_mirror row_mask:0xf bank_mask:0xf
	s_nop 1
	v_add_f32_dpp v62, v62, v62 row_mirror row_mask:0xf bank_mask:0xf
	v_fmamk_f32 v62, v62, 0x3c000000, v118
	v_rsq_f32_e32 v62, v62
	s_nop 0
	v_pk_mul_f32 v[46:47], v[46:47], v[62:63] op_sel_hi:[1,0]
	v_pk_mul_f32 v[48:49], v[48:49], v[62:63] op_sel_hi:[1,0]
	v_pk_mul_f32 v[42:43], v[42:43], v[62:63] op_sel_hi:[1,0]
	v_pk_mul_f32 v[44:45], v[44:45], v[62:63] op_sel_hi:[1,0]
	s_waitcnt vmcnt(0)
	v_pk_mul_f32 v[42:43], v[232:233], v[42:43]
	v_pk_mul_f32 v[46:47], v[236:237], v[46:47]
	v_lshlrev_b32_e32 v58, 16, v69
	v_and_b32_e32 v59, 0xffff0000, v69
	v_pk_mul_f32 v[48:49], v[238:239], v[48:49]
	v_lshlrev_b32_e32 v54, 16, v67
	v_pk_mul_f32 v[48:49], v[48:49], v[58:59]
	v_lshlrev_b32_e32 v58, 16, v66
	v_and_b32_e32 v59, 0xffff0000, v66
	v_and_b32_e32 v55, 0xffff0000, v67
	v_pk_mul_f32 v[44:45], v[234:235], v[44:45]
	v_pk_mul_f32 v[46:47], v[46:47], v[64:65]
	v_pk_mul_f32 v[42:43], v[42:43], v[58:59]
	v_pk_mul_f32 v[44:45], v[44:45], v[54:55]
	v_cvt_pk_bf16_f32 v42, v42, v43
	v_cvt_pk_bf16_f32 v43, v44, v45
	v_cvt_pk_bf16_f32 v44, v46, v47
	v_cvt_pk_bf16_f32 v45, v48, v49
	global_store_dwordx4 v[102:103], v[42:45], off offset:1536
	ds_read_b128 v[42:45], v119
	ds_read_b128 v[46:49], v119 offset:16
	v_lshlrev_b32_e32 v64, 16, v52
	v_and_b32_e32 v65, 0xffff0000, v52
	v_lshlrev_b32_e32 v52, 16, v53
	s_waitcnt lgkmcnt(1)
	v_pk_mul_f32 v[54:55], v[44:45], v[44:45]
	v_pk_mul_f32 v[56:57], v[42:43], v[42:43]
	v_and_b32_e32 v53, 0xffff0000, v53
	v_pk_mov_b32 v[58:59], v[56:57], v[54:55] op_sel:[1,0]
	v_mov_b32_e32 v57, v55
	v_pk_add_f32 v[54:55], v[58:59], v[56:57]
	s_waitcnt lgkmcnt(0)
	v_pk_mul_f32 v[56:57], v[48:49], v[48:49]
	v_pk_mul_f32 v[58:59], v[46:47], v[46:47]
	v_mov_b32_e32 v60, v56
	v_mov_b32_e32 v61, v58
	v_mov_b32_e32 v58, v57
	v_pk_add_f32 v[56:57], v[60:61], v[58:59]
	v_add_f32_e32 v54, v54, v55
	v_add_f32_e32 v54, v54, v57
	v_add_f32_e32 v54, v56, v54
	s_nop 1
	v_add_f32_dpp v54, v54, v54 quad_perm:[1,0,3,2] row_mask:0xf bank_mask:0xf
	s_nop 1
	v_add_f32_dpp v54, v54, v54 quad_perm:[2,3,0,1] row_mask:0xf bank_mask:0xf
	s_nop 1
	v_add_f32_dpp v62, v54, v54 row_half_mirror row_mask:0xf bank_mask:0xf
	s_nop 1
	v_add_f32_dpp v62, v62, v62 row_mirror row_mask:0xf bank_mask:0xf
	v_fmamk_f32 v62, v62, 0x3c000000, v118
	v_rsq_f32_e32 v62, v62
	s_nop 0
	v_pk_mul_f32 v[48:49], v[48:49], v[62:63] op_sel_hi:[1,0]
	v_pk_mul_f32 v[46:47], v[46:47], v[62:63] op_sel_hi:[1,0]
	v_pk_mul_f32 v[42:43], v[42:43], v[62:63] op_sel_hi:[1,0]
	v_pk_mul_f32 v[44:45], v[44:45], v[62:63] op_sel_hi:[1,0]
	v_pk_mul_f32 v[42:43], v[232:233], v[42:43]
	v_pk_mul_f32 v[48:49], v[238:239], v[48:49]
	v_pk_mul_f32 v[46:47], v[236:237], v[46:47]
	v_pk_mul_f32 v[48:49], v[48:49], v[52:53]
	v_lshlrev_b32_e32 v52, 16, v50
	v_and_b32_e32 v53, 0xffff0000, v50
	v_lshlrev_b32_e32 v50, 16, v51
	v_and_b32_e32 v51, 0xffff0000, v51
	v_pk_mul_f32 v[44:45], v[234:235], v[44:45]
	v_pk_mul_f32 v[46:47], v[46:47], v[64:65]
	v_pk_mul_f32 v[42:43], v[42:43], v[52:53]
	v_pk_mul_f32 v[44:45], v[44:45], v[50:51]
	v_cvt_pk_bf16_f32 v42, v42, v43
	v_cvt_pk_bf16_f32 v43, v44, v45
	v_cvt_pk_bf16_f32 v44, v46, v47
	v_cvt_pk_bf16_f32 v45, v48, v49
	global_store_dwordx4 v[100:101], v[42:45], off offset:1536
	s_waitcnt vmcnt(1)
	v_lshl_or_b32 v129, v185, 16, v184
	v_lshl_or_b32 v127, v190, 16, v191
	v_lshl_or_b32 v131, v192, 16, v188
	v_lshl_or_b32 v128, v194, 16, v189
	v_lshl_or_b32 v133, v196, 16, v195
	v_lshl_or_b32 v135, v203, 16, v202
	v_lshl_or_b32 v134, v214, 16, v215
	v_lshl_or_b32 v34, v187, 16, v186
	v_lshl_or_b32 v35, v199, 16, v193
	v_lshl_or_b32 v36, v200, 16, v197
	v_lshl_or_b32 v130, v198, 16, v201
	v_lshl_or_b32 v37, v205, 16, v204
	v_lshl_or_b32 v132, v206, 16, v207
	v_lshl_or_b32 v137, v209, 16, v208
	v_lshl_or_b32 v38, v211, 16, v210
	v_lshl_or_b32 v139, v216, 16, v212
	v_lshl_or_b32 v136, v218, 16, v213
	v_lshl_or_b32 v141, v220, 16, v219
	v_lshl_or_b32 v39, v223, 16, v217
	v_lshl_or_b32 v40, v224, 16, v221
	v_lshl_or_b32 v138, v222, 16, v225
	v_lshl_or_b32 v142, v227, 16, v226
	v_lshl_or_b32 v41, v229, 16, v228
	v_lshl_or_b32 v140, v230, 16, v231
	v_mov_b32_e32 v46, v127
	v_mov_b32_e32 v47, v128
	v_mov_b32_e32 v49, v130
	v_mov_b32_e32 v51, v132
	v_mov_b32_e32 v52, v134
	v_mov_b32_e32 v53, v136
	v_mov_b32_e32 v54, v138
	v_mov_b32_e32 v48, v140
	v_mov_b32_e32 v42, v129
	v_mov_b32_e32 v43, v131
	v_mov_b32_e32 v44, v133
	v_mov_b32_e32 v45, v135
	v_mov_b32_e32 v50, v137
	v_mov_b32_e32 v55, v139
	v_mov_b32_e32 v56, v141
	v_mov_b32_e32 v57, v142
	s_cbranch_scc0 .LBB0_1168
